# sample tile map v2: each XCD takes the 64-column tiles of a 256-column weight tile its own main-GEMM units just streamed (x' = 4(x&1) + (x>>1))
# speedup vs baseline: 1.0054x; 1.0052x over previous
; #define LAS __attribute__((address_space(3)))
; template <bool GATE>
; __device__ __forceinline__ void sample_gemm_res(LAS unsigned char* lds, const bf16* Amat, const bf16* Bt, const bf16* Hin, bf16* Hout, float* rss_out, const bf16* PP, const float* rss_in, int bid, int tid) {
;     const int wave = tid >> 6, lane = tid & 63, lr = lane & 15, kg = lane >> 4;
;   for (int tile = bid; tile < 256; tile += (int)gridDim.x) {
;     const int m0 = TP + (tile & 7) * 64, n0 = (tile >> 3) * 64;
;     const bf16x8* ap = (const bf16x8*)(Amat + (size_t)(m0 + lr) * 2048 + wave * 256 + 8 * kg);
;     const bf16x8* bp = (const bf16x8*)(Bt + (size_t)(n0 + lr) * 2048 + wave * 256 + 8 * kg);
;     const int erow = m0 + (tid >> 3); const size_t ep = (size_t)erow * 2048 + n0 + (tid & 7) * 8;
.LBB0_64:
	v_mov_b32_e32 v0, v183
	s_and_b64 vcc, exec, s[40:41]
	s_cbranch_vccnz .LBB0_71
	v_and_b32_e32 v8, 64, v216
	v_xor_b32_e32 v7, 1, v216
	v_add_u32_e32 v8, 64, v8
	v_cmp_lt_i32_e32 vcc, v7, v8
	s_waitcnt vmcnt(0)
	v_and_b32_e32 v75, 15, v0
	v_bfe_u32 v4, v0, 4, 2
	v_cndmask_b32_e32 v7, v216, v7, vcc
	v_lshlrev_b32_e32 v90, 2, v7
	v_xor_b32_e32 v7, 2, v216
	v_lshlrev_b32_e32 v2, 2, v0
	v_ashrrev_i32_e32 v88, 3, v0
	v_and_b32_e32 v5, 7, v0
	v_and_b32_e32 v0, 0x3fffffc0, v0
	v_cmp_lt_i32_e32 vcc, v7, v8
	v_lshl_or_b32 v0, v4, 2, v0
	s_load_dwordx2 s[0:1], s[60:61], 0x148
	v_cndmask_b32_e32 v7, v216, v7, vcc
	v_and_b32_e32 v2, 0xffffff00, v2
	v_lshlrev_b32_e32 v6, 2, v75
	v_lshlrev_b32_e32 v91, 2, v7
	v_xor_b32_e32 v7, 4, v216
	v_mul_lo_u32 v0, v0, s30
	s_waitcnt lgkmcnt(0)
	v_ashrrev_i32_e32 v3, 31, v2
	v_cmp_lt_i32_e32 vcc, v7, v8
	v_add3_u32 v93, 0, v6, v0
	v_lshlrev_b32_e32 v0, 4, v4
	v_lshlrev_b32_e32 v74, 3, v5
	v_lshl_add_u32 v89, v5, 5, 0
	v_cndmask_b32_e32 v7, v216, v7, vcc
	v_cmp_eq_u32_e32 vcc, 0, v5
	v_mul_lo_u32 v94, v88, s30
	v_lshl_add_u64 v[4:5], s[56:57], 0, v[0:1]
	v_lshlrev_b64 v[2:3], 1, v[2:3]
	v_lshlrev_b32_e32 v92, 2, v7
	v_add_u32_e32 v6, 0x10400, v94
	v_add_u32_e32 v7, 0x14500, v94
	v_add_u32_e32 v8, 0x18600, v94
	v_add_u32_e32 v9, 0x1c700, v94
	v_lshl_add_u64 v[4:5], v[4:5], 0, v[2:3]
	v_or_b32_e32 v2, v2, v0
	v_readlane_b32 s6, v254, 39
	v_lshl_add_u64 v[76:77], s[0:1], 0, v[4:5]
	v_lshl_add_u64 v[78:79], s[0:1], 0, v[2:3]
	v_or_b32_e32 v95, 0x2000, v75
	s_lshl_b32 s2, s6, 6
	v_add_u32_e32 v96, v89, v6
	v_add_u32_e32 v97, v89, v7
	v_add_u32_e32 v98, v89, v8
	v_add_u32_e32 v99, v89, v9
	s_mov_b32 s3, s59
	s_cmpk_lg_i32 s92, 0x100
	s_cbranch_scc1 .Lsmp_map_keep67
	s_and_b32 s4, s6, 7
	s_lshr_b32 s5, s6, 3
	s_and_b32 s2, s4, 1
	s_lshl_b32 s2, s2, 2
	s_lshr_b32 s4, s4, 1
	s_add_i32 s4, s4, s2
	s_lshl_b32 s4, s4, 2
	s_lshr_b32 s2, s5, 3
	s_add_i32 s4, s4, s2
	s_and_b32 s5, s5, 7
	s_lshl_b32 s4, s4, 3
	s_or_b32 s6, s4, s5
	s_lshl_b32 s2, s6, 6
	s_lshl_b32 s3, s6, 3

; #define LAS __attribute__((address_space(3)))
; template <bool GATE>
; __device__ __forceinline__ void sample_gemm_res(LAS unsigned char* lds, const bf16* Amat, const bf16* Bt, const bf16* Hin, bf16* Hout, float* rss_out, const bf16* PP, const float* rss_in, int bid, int tid) {
;     const int wave = tid >> 6, lane = tid & 63, lr = lane & 15, kg = lane >> 4;
;   for (int tile = bid; tile < 256; tile += (int)gridDim.x) {
;     const int m0 = TP + (tile & 7) * 64, n0 = (tile >> 3) * 64;
;     const bf16x8* ap = (const bf16x8*)(Amat + (size_t)(m0 + lr) * 2048 + wave * 256 + 8 * kg);
;     const bf16x8* bp = (const bf16x8*)(Bt + (size_t)(n0 + lr) * 2048 + wave * 256 + 8 * kg);
;     const int erow = m0 + (tid >> 3); const size_t ep = (size_t)erow * 2048 + n0 + (tid & 7) * 8;
.LBB0_112:
	v_mov_b32_e32 v0, v183
	s_and_b64 vcc, exec, s[40:41]
	s_cbranch_vccnz .LBB0_119
	v_and_b32_e32 v8, 64, v216
	v_xor_b32_e32 v7, 1, v216
	v_add_u32_e32 v8, 64, v8
	v_cmp_lt_i32_e32 vcc, v7, v8
	s_waitcnt vmcnt(0)
	v_and_b32_e32 v71, 15, v0
	v_bfe_u32 v4, v0, 4, 2
	v_cndmask_b32_e32 v7, v216, v7, vcc
	v_lshlrev_b32_e32 v86, 2, v7
	v_xor_b32_e32 v7, 2, v216
	v_lshlrev_b32_e32 v2, 2, v0
	v_ashrrev_i32_e32 v84, 3, v0
	v_and_b32_e32 v5, 7, v0
	v_and_b32_e32 v0, 0x3fffffc0, v0
	v_cmp_lt_i32_e32 vcc, v7, v8
	v_lshl_or_b32 v0, v4, 2, v0
	v_lshlrev_b32_e32 v6, 2, v71
	v_cndmask_b32_e32 v7, v216, v7, vcc
	v_lshlrev_b32_e32 v87, 2, v7
	v_xor_b32_e32 v7, 4, v216
	v_mul_lo_u32 v0, v0, s30
	s_add_u32 s0, s14, s52
	v_cmp_lt_i32_e32 vcc, v7, v8
	v_add3_u32 v89, 0, v6, v0
	s_addc_u32 s1, 0, s53
	v_lshlrev_b32_e32 v0, 4, v4
	v_lshlrev_b32_e32 v70, 3, v5
	v_lshl_add_u32 v85, v5, 5, 0
	v_cndmask_b32_e32 v7, v216, v7, vcc
	v_cmp_eq_u32_e32 vcc, 0, v5
	v_lshl_add_u64 v[4:5], s[0:1], 0, v[0:1]
	s_load_dwordx2 s[0:1], s[60:61], 0x148
	v_and_b32_e32 v2, 0xffffff00, v2
	s_waitcnt lgkmcnt(0)
	v_ashrrev_i32_e32 v3, 31, v2
	v_mul_lo_u32 v90, v84, s30
	v_lshlrev_b64 v[2:3], 1, v[2:3]
	v_lshlrev_b32_e32 v88, 2, v7
	v_add_u32_e32 v6, 0x10400, v90
	v_add_u32_e32 v7, 0x14500, v90
	v_add_u32_e32 v8, 0x18600, v90
	v_add_u32_e32 v9, 0x1c700, v90
	v_lshl_add_u64 v[4:5], v[4:5], 0, v[2:3]
	v_or_b32_e32 v2, v2, v0
	v_readlane_b32 s6, v254, 39
	v_lshl_add_u64 v[72:73], s[0:1], 0, v[4:5]
	v_lshl_add_u64 v[74:75], s[0:1], 0, v[2:3]
	v_or_b32_e32 v91, 0x2000, v71
	s_lshl_b32 s2, s6, 6
	v_add_u32_e32 v92, v85, v6
	v_add_u32_e32 v93, v85, v7
	v_add_u32_e32 v94, v85, v8
	v_add_u32_e32 v95, v85, v9
	s_mov_b32 s3, s59
	s_cmpk_lg_i32 s92, 0x100
	s_cbranch_scc1 .Lsmp_map_keep115
	s_and_b32 s4, s6, 7
	s_lshr_b32 s5, s6, 3
	s_and_b32 s2, s4, 1
	s_lshl_b32 s2, s2, 2
	s_lshr_b32 s4, s4, 1
	s_add_i32 s4, s4, s2
	s_lshl_b32 s4, s4, 2
	s_lshr_b32 s2, s5, 3
	s_add_i32 s4, s4, s2
	s_and_b32 s5, s5, 7
	s_lshl_b32 s4, s4, 3
	s_or_b32 s6, s4, s5
	s_lshl_b32 s2, s6, 6
	s_lshl_b32 s3, s6, 3
